# phase 0 LoRA weight transposes: a thread's four element loads issued together from block-uniform scalar row bases instead of load->vmcnt(0)->store per element
# baseline (speedup 1.0000x reference)
.LBB0_41:
	v_lshl_or_b32 v1, s2, 9, v0
	s_mov_b32 s6, 0x70000
	v_cmp_gt_i32_e32 vcc, s6, v1
	s_and_saveexec_b64 s[6:7], vcc
	s_cbranch_execz .LBB0_52
	s_waitcnt lgkmcnt(0)
	s_lshr_b32 s16, s2, 1
	s_and_b32 s17, s2, 1
	s_lshl_b32 s17, s17, 9
	v_add_u32_e32 v1, s17, v0
	v_lshlrev_b32_e32 v2, 2, v1
	v_mul_u32_u24_e32 v3, 0xc0, v1
	v_lshlrev_b32_e32 v4, 9, v1
	s_cmp_lt_u32 s16, 96
	s_cbranch_scc0 .Llr_a0
	s_lshl_b32 s18, s16, 12
	s_add_u32 s20, s46, s18
	s_addc_u32 s21, s47, 0
	s_lshl_b32 s18, s16, 1
	s_add_u32 s18, s18, 0x7600000
	s_add_u32 s22, s70, s18
	s_addc_u32 s23, s71, 0
	v_mov_b32_e32 v10, v3
	s_branch .Llr_j1
.Llr_a0:
	s_sub_u32 s19, s16, 96
	s_lshl_b32 s18, s19, 12
	s_add_u32 s20, s50, s18
	s_addc_u32 s21, s51, 0
	s_lshl_b32 s18, s19, 1
	s_add_u32 s18, s18, 0x7630000
	s_add_u32 s22, s70, s18
	s_addc_u32 s23, s71, 0
	v_mov_b32_e32 v10, v3
.Llr_j1:
	s_cmp_lt_u32 s16, 64
	s_cbranch_scc0 .Llr_g1
	s_add_u32 s19, s16, 32
	s_lshl_b32 s18, s19, 12
	s_add_u32 s24, s50, s18
	s_addc_u32 s25, s51, 0
	s_lshl_b32 s18, s19, 1
	s_add_u32 s18, s18, 0x7630000
	s_add_u32 s26, s70, s18
	s_addc_u32 s27, s71, 0
	v_mov_b32_e32 v11, v3
	s_branch .Llr_j2
.Llr_g1:
	s_sub_u32 s19, s16, 64
	s_lshl_b32 s18, s19, 12
	s_add_u32 s24, s52, s18
	s_addc_u32 s25, s53, 0
	s_lshl_b32 s18, s19, 1
	s_add_u32 s18, s18, 0x7660000
	s_add_u32 s26, s70, s18
	s_addc_u32 s27, s71, 0
	v_mov_b32_e32 v11, v4
.Llr_j2:
	s_add_u32 s19, s16, 64
	s_lshl_b32 s18, s19, 12
	s_add_u32 s28, s52, s18
	s_addc_u32 s29, s53, 0
	s_lshl_b32 s18, s19, 1
	s_add_u32 s18, s18, 0x7660000
	s_add_u32 s30, s70, s18
	s_addc_u32 s31, s71, 0
	v_mov_b32_e32 v12, v4
	global_load_dword v5, v2, s[20:21]
	global_load_dword v6, v2, s[24:25]
	global_load_dword v7, v2, s[28:29]
	s_cmp_lt_u32 s16, 64
	s_cbranch_scc0 .Llr_no3
	s_add_u32 s19, s16, 0xc0
	s_lshl_b32 s18, s19, 12
	s_add_u32 s12, s52, s18
	s_addc_u32 s13, s53, 0
	s_lshl_b32 s18, s19, 1
	s_add_u32 s18, s18, 0x7660000
	s_add_u32 s14, s70, s18
	s_addc_u32 s15, s71, 0
	global_load_dword v8, v2, s[12:13]
.Llr_no3:
	s_waitcnt vmcnt(0)
	v_cvt_pk_bf16_f32 v5, v5, v5
	global_store_short v10, v5, s[22:23]
	v_cvt_pk_bf16_f32 v6, v6, v6
	global_store_short v11, v6, s[26:27]
	v_cvt_pk_bf16_f32 v7, v7, v7
	global_store_short v12, v7, s[30:31]
	s_cmp_lt_u32 s16, 64
	s_cbranch_scc0 .Llr_done
	v_cvt_pk_bf16_f32 v8, v8, v8
	global_store_short v4, v8, s[14:15]
.Llr_done:
.LBB0_52:
	s_or_b64 exec, exec, s[6:7]
	v_lshrrev_b32_e32 v1, 6, v0
	v_lshl_or_b32 v2, s2, 3, v1
	s_movk_i32 s6, 0x2000
	v_cmp_gt_i32_e32 vcc, s6, v2
	s_and_saveexec_b64 s[10:11], vcc
	s_cbranch_execz .LBB0_57
	v_mbcnt_lo_u32_b32 v1, -1, 0
	v_mbcnt_hi_u32_b32 v3, -1, v1
	v_and_b32_e32 v1, 64, v3
	v_add_u32_e32 v4, 64, v1
	v_xor_b32_e32 v1, 32, v3
	v_cmp_lt_i32_e32 vcc, v1, v4
	v_xor_b32_e32 v5, 16, v3
	v_and_b32_e32 v15, 63, v0
	v_cndmask_b32_e32 v1, v3, v1, vcc
	v_cmp_lt_i32_e32 vcc, v5, v4
	s_waitcnt lgkmcnt(0)
	s_lshl_b32 s12, s3, 3
	s_ashr_i32 s13, s12, 31
	v_cndmask_b32_e32 v5, v3, v5, vcc
	v_lshlrev_b32_e32 v10, 2, v5
	v_xor_b32_e32 v5, 8, v3
	v_cmp_lt_i32_e32 vcc, v5, v4
	s_mov_b64 s[18:19], 0x1000
	v_lshlrev_b32_e32 v1, 2, v1
	v_cndmask_b32_e32 v5, v3, v5, vcc
	v_lshlrev_b32_e32 v11, 2, v5
	v_xor_b32_e32 v5, 4, v3
	v_cmp_lt_i32_e32 vcc, v5, v4
	v_cmp_eq_u32_e64 s[6:7], 0, v15
	s_lshl_b64 s[14:15], s[12:13], 2
	v_cndmask_b32_e32 v5, v3, v5, vcc
	v_lshlrev_b32_e32 v12, 2, v5
	v_xor_b32_e32 v5, 2, v3
	v_cmp_lt_i32_e32 vcc, v5, v4
	s_lshl_b64 s[16:17], s[12:13], 12
	s_mov_b64 s[20:21], 0
	v_cndmask_b32_e32 v5, v3, v5, vcc
	v_lshlrev_b32_e32 v13, 2, v5
	v_xor_b32_e32 v5, 1, v3
	v_cmp_lt_i32_e32 vcc, v5, v4
	s_mov_b32 s3, 0x10900000
	s_movk_i32 s24, 0x1fff
	v_cndmask_b32_e32 v3, v3, v5, vcc
	v_lshlrev_b32_e32 v14, 2, v3
	v_ashrrev_i32_e32 v3, 31, v2
	v_lshlrev_b64 v[8:9], 13, v[2:3]
	v_lshl_or_b32 v8, v15, 4, v8
	v_mov_b64_e32 v[4:5], 0x14900000
	v_lshlrev_b64 v[6:7], 12, v[2:3]
	v_lshl_add_u64 v[8:9], s[36:37], 0, v[8:9]
	v_lshl_add_u64 v[4:5], v[2:3], 2, v[4:5]
	v_lshl_or_b32 v6, v15, 3, v6
	v_lshl_add_u64 v[8:9], v[8:9], 0, s[18:19]
	s_lshl_b64 s[18:19], s[12:13], 13
	v_mov_b32_e32 v3, 0x358637bd
	s_mov_b32 s13, 0x800000
	s_branch .LBB0_55

.Lat_pv_done:
	s_nop 7
	v_cvt_pk_bf16_f32 v22, v240, v240
	v_cvt_pk_bf16_f32 v23, v241, v241
	v_cvt_pk_bf16_f32 v24, v242, v242
	v_cvt_pk_bf16_f32 v25, v243, v243
	v_cvt_pk_bf16_f32 v26, v244, v244
	v_cvt_pk_bf16_f32 v27, v245, v245
	v_cvt_pk_bf16_f32 v28, v246, v246
	v_cvt_pk_bf16_f32 v29, v247, v247
	v_cvt_pk_bf16_f32 v134, v248, v248
	v_cvt_pk_bf16_f32 v135, v249, v249
	v_cvt_pk_bf16_f32 v136, v250, v250
	v_cvt_pk_bf16_f32 v137, v251, v251
	v_cvt_pk_bf16_f32 v138, v120, v120
	v_cvt_pk_bf16_f32 v139, v121, v121
	v_cvt_pk_bf16_f32 v150, v122, v122
	v_cvt_pk_bf16_f32 v151, v123, v123
	global_store_short v17, v22, s[20:21]
	global_store_short v17, v23, s[20:21] offset:2048
	global_store_short v18, v24, s[20:21]
	global_store_short v18, v25, s[20:21] offset:2048
	global_store_short v17, v26, s[20:21] offset:32
	global_store_short v17, v27, s[20:21] offset:2080
	global_store_short v18, v28, s[20:21] offset:32
	global_store_short v18, v29, s[20:21] offset:2080
	global_store_short v17, v134, s[20:21] offset:64
	global_store_short v17, v135, s[20:21] offset:2112
	global_store_short v18, v136, s[20:21] offset:64
	global_store_short v18, v137, s[20:21] offset:2112
	global_store_short v17, v138, s[20:21] offset:96
	global_store_short v17, v139, s[20:21] offset:2144
	global_store_short v18, v150, s[20:21] offset:96
	global_store_short v18, v151, s[20:21] offset:2144
	s_add_u32 s3, s3, s6
	s_cmp_lt_u32 s3, 0x2000
	s_cbranch_scc1 .Lat_loop
	v_and_b32_e32 v10, 15, v0
	s_add_u32 s74, s0, 0xd8
	s_addc_u32 s75, s1, 0
	v_mov_b64_e32 v[2:3], s[74:75]
	s_mov_b64 s[64:65], exec
	s_nop 0
	s_nop 0
	s_nop 0
	s_nop 0
	s_nop 0
	s_nop 0
	s_nop 0
	s_nop 0
	s_nop 0
	s_nop 0
	s_nop 0
	s_nop 0
	s_nop 0
	s_nop 0
	s_nop 0
	s_nop 0
	s_nop 0
	s_nop 0
	s_nop 0
	s_nop 0
	s_nop 0
	s_nop 0
	s_nop 0
	s_nop 0
	s_nop 0
	s_nop 0
	s_nop 0
	s_nop 0
	s_nop 0
.LBB0_388:
	s_or_b64 exec, exec, s[64:65]
	s_sub_i32 s6, s2, 32
	v_readfirstlane_b32 s7, v0
	s_cmpk_gt_u32 s6, 0x17f
	v_lshlrev_b32_e32 v157, 2, v0
	s_waitcnt lgkmcnt(0)
	s_barrier
	s_cbranch_scc1 .LBB0_405
	v_lshrrev_b32_e32 v1, 5, v0
	global_load_dword v15, v[2:3], off
	v_and_b32_e32 v2, 4, v1
	v_lshrrev_b32_e32 v1, 1, v0
	v_bfe_u32 v3, v0, 2, 2
	v_and_b32_e32 v1, 24, v1
	s_add_u32 s8, s70, 0x10900000
	v_or3_b32 v2, v2, v3, v1
	v_lshlrev_b32_e32 v3, 4, v0
	s_addc_u32 s9, s71, 0
	v_or_b32_e32 v11, 0x2000, v3
	s_add_u32 s10, s70, 0x2e00000
	v_lshrrev_b32_e32 v4, 7, v11
	s_movk_i32 s3, 0x60
	s_waitcnt vmcnt(18)
	v_bfe_u32 v14, v0, 2, 4
	s_movk_i32 s12, 0x70
	s_addc_u32 s11, s71, 0
	v_and_or_b32 v5, v4, s3, v2
	v_and_or_b32 v4, v4, s12, v14
	s_and_b32 s12, s2, 7
	s_lshr_b32 s13, s6, 3
	s_mul_i32 s12, s12, 48
	s_add_i32 s12, s12, s13
	s_mul_i32 s13, s12, 0xaaab
	s_lshr_b32 s13, s13, 22
	s_lshl_b32 s14, s13, 3
	s_mulk_i32 s13, 0x60
	s_sub_i32 s12, s12, s13
	s_and_b32 s13, s12, 7
	v_and_b32_e32 v6, 32, v0
	s_or_b32 s18, s14, s13
	s_lshr_b32 s22, s7, 6
	v_bitop3_b32 v12, v3, v6, 48 bitop3:0x6c
	v_and_b32_e32 v13, 64, v0
	s_bfe_u32 s19, s12, 0x50003
	s_and_b32 s12, s18, 0x1fff
	s_mov_b32 s13, 0
	s_lshr_b32 s24, s7, 8
	s_lshl_b32 s42, s22, 10
	v_or_b32_e32 v3, v12, v13
	s_lshl_b64 s[14:15], s[12:13], 20
	s_lshl_b32 s12, s19, 20
	v_lshl_or_b32 v134, v4, 12, v3
	v_lshrrev_b32_e32 v4, 3, v0
	s_add_u32 s30, s10, s12
	v_and_or_b32 v2, v4, 32, v2
	s_addc_u32 s31, s11, 0
	s_add_i32 s12, s42, 0
	v_lshl_or_b32 v136, v2, 12, v3
	s_add_i32 m0, s12, 0x10000
	v_lshl_or_b32 v132, v5, 12, v3
	global_load_lds_dwordx4 v136, s[30:31]
	s_add_i32 m0, s12, 0x12000
	s_add_u32 s16, s30, 0x80000
	global_load_lds_dwordx4 v132, s[30:31]
	s_addc_u32 s17, s31, 0
	s_add_i32 m0, s12, 0x14000
	v_and_or_b32 v2, v4, 48, v14
	global_load_lds_dwordx4 v136, s[16:17]
	s_add_i32 m0, s12, 0x16000
	s_add_u32 s44, s8, s14
	s_addc_u32 s45, s9, s15
	s_add_i32 s78, s12, 0x2000
	v_lshl_or_b32 v138, v2, 12, v3
	global_load_lds_dwordx4 v132, s[16:17]
	s_mov_b32 m0, s12
	s_add_u32 s14, s44, 0x80000
	global_load_lds_dwordx4 v138, s[44:45]
	s_mov_b32 m0, s78
	s_addc_u32 s15, s45, 0
	s_add_i32 s79, s12, 0x4000
	global_load_lds_dwordx4 v134, s[44:45]
	s_mov_b32 m0, s79
	s_add_i32 s80, s12, 0x6000
	global_load_lds_dwordx4 v138, s[14:15]
	s_mov_b32 m0, s80
	v_mov_b32_e32 v137, 0
	global_load_lds_dwordx4 v134, s[14:15]
	v_mov_b32_e32 v133, v137
	v_mov_b32_e32 v139, v137
	v_mov_b32_e32 v135, v137
	s_cmp_eq_u32 s24, 1
	v_lshl_add_u64 v[8:9], s[30:31], 0, v[136:137]
	v_lshl_add_u64 v[4:5], s[30:31], 0, v[132:133]
	s_mov_b64 s[14:15], 0x80000
	v_lshl_add_u64 v[2:3], s[44:45], 0, v[138:139]
	s_cselect_b64 s[16:17], -1, 0
	s_cmp_lg_u32 s24, 1
	v_lshl_add_u64 v[6:7], s[44:45], 0, v[134:135]
	s_cbranch_scc1 .LBB0_391
	s_barrier
